# v008 + gMLP unit loop no longer waits for the previous unit's stores at its top (vmcnt(8))
# speedup vs baseline: 1.0138x; 1.0097x over previous
; #define LAS __attribute__((address_space(3)))
; __device__ __forceinline__ void gmlp_load(GmlpRegs& R, const bf16_t* zb, const bf16_t* wsb, const float* bsall, int u, int tid, int t, int h, int cb0) {
;     const int b = u / 96, rem = u % 96, n = rem / 6, g = rem % 6;
;     const bf16_t* zrows = zb + ((size_t)b * SEQ + n * 128) * NMIX0;
;     const bf16_t* urow = zrows + (size_t)t * NMIX0 + g * 128 + 4 * h;
; #pragma unroll
;     for (int i = 0; i < 8; ++i) R.uv[i] = *(const u32x2*)(urow + (cb0 + (i >> 2)) * 32 + 8 * (i & 3));
;     const bf16_t* wrow = wsb + (size_t)g * 128 * 128 + (size_t)t * 128 + 8 * h;
; #pragma unroll
;     for (int i = 0; i < 8; ++i) R.w[i] = *(const u32x4*)(wrow + 16 * i);
;     R.bias = bsall[g * 128 + t];
;     const bf16_t* vgp = zrows + (size_t)(tid >> 2) * NMIX0 + 768 + g * 128 + (tid & 3) * 32;
; #pragma unroll
;     for (int j = 0; j < 4; ++j) R.v[j] = *(const u32x4*)(vgp + 8 * j);
; }
; __device__ __forceinline__ void gmlp_phase(LAS unsigned char* lds, const bf16_t* zb, const bf16_t* wsb, const float* bsall, const float* vgall, bf16_t* cat, int vcu, int G, const int tid) {
;     constexpr int GOFF = 49152;
;     if (vcu >= 1536) return;
;     if (tid < 192) *(LAS f32x4*)(lds + GOFF + tid * 16) = *(const f32x4*)(vgall + tid * 4);
;     const int w = __builtin_amdgcn_readfirstlane(tid >> 6), lane = tid & 63, r = lane & 31, h = lane >> 5;
;     const int tb = w & 3, cb0 = (w >> 2) * 2; int t = 32 * tb + r; asm volatile("" : "+v"(t));
;     int u = vcu;
;     GmlpRegs A; gmlp_load(A, zb, wsb, bsall, u, tid, t, h, cb0);
;     __syncthreads();
; #pragma unroll 1
;     for (;;) {
;         const int un = u + G; const bool hn = un < 1536;
;         GmlpRegs B; gmlp_load(B, zb, wsb, bsall, hn ? un : u, tid, t, h, cb0);
.LBB0_68:
	s_or_b64 exec, exec, s[6:7]
	s_add_u32 s6, s18, 0x192c4000
	v_readfirstlane_b32 s8, v218
	s_addc_u32 s7, s19, 0
	s_ashr_i32 s9, s8, 7
	s_lshr_b32 s8, s8, 1
	s_and_b32 s8, s8, 0x60
	v_and_or_b32 v114, v218, 31, s8
	s_mul_hi_i32 s8, s33, 0x2aaaaaab
	s_and_b32 s23, s9, -2
	s_lshr_b32 s9, s8, 31
	s_ashr_i32 s8, s8, 4
	s_add_i32 s8, s8, s9
	s_mul_i32 s9, s8, 0x60
	s_sub_i32 s9, s33, s9
	s_mul_i32 s10, s9, 43
	s_bfe_u32 s11, s10, 0x1000f
	s_bfe_u32 s10, s10, 0x80008
	s_add_i32 s10, s10, s11
	s_sext_i32_i8 s11, s10
	s_mul_i32 s10, s10, 6
	s_sub_i32 s10, s9, s10
	s_ashr_i32 s9, s8, 31
	s_lshl_b32 s11, s11, 7
	s_lshl_b64 s[8:9], s[8:9], 11
	s_ashr_i32 s35, s11, 31
	s_add_u32 s8, s8, s11
	s_addc_u32 s9, s9, s35
	s_mulk_i32 s9, 0xe00
	s_mul_hi_u32 s11, s8, 0xe00
	s_add_i32 s11, s11, s9
	s_mulk_i32 s8, 0xe00
	s_add_u32 s8, s24, s8
	s_addc_u32 s9, s25, s11
	v_mov_b64_e32 v[2:3], s[8:9]
	s_movk_i32 s38, 0xe00
	s_sext_i32_i8 s34, s10
	v_mad_i64_i32 v[4:5], s[8:9], v114, s38, v[2:3]
	s_lshl_b32 s8, s34, 7
	s_ashr_i32 s9, s8, 31
	v_lshrrev_b32_e32 v12, 5, v190
	s_lshl_b64 s[34:35], s[8:9], 1
	v_lshl_add_u64 v[4:5], v[4:5], 0, s[34:35]
	v_lshlrev_b32_e32 v0, 3, v12
	s_lshl_b32 s36, s23, 5
	s_bfe_i64 s[10:11], s[10:11], 0x80000
	v_lshl_add_u64 v[4:5], v[4:5], 0, v[0:1]
	s_ashr_i32 s37, s36, 31
	s_lshl_b64 s[10:11], s[10:11], 15
	v_ashrrev_i32_e32 v115, 31, v114
	v_lshl_add_u64 v[4:5], s[36:37], 1, v[4:5]
	s_add_u32 s10, s6, s10
	global_load_dwordx2 v[160:161], v[4:5], off
	global_load_dwordx2 v[162:163], v[4:5], off offset:16
	global_load_dwordx2 v[164:165], v[4:5], off offset:32
	global_load_dwordx2 v[134:135], v[4:5], off offset:48
	global_load_dwordx2 v[132:133], v[4:5], off offset:64
	global_load_dwordx2 v[130:131], v[4:5], off offset:80
	global_load_dwordx2 v[128:129], v[4:5], off offset:96
	global_load_dwordx2 v[126:127], v[4:5], off offset:112
	s_addc_u32 s11, s7, s11
	v_lshlrev_b64 v[4:5], 8, v[114:115]
	v_lshl_add_u64 v[6:7], s[10:11], 0, v[4:5]
	v_lshlrev_b32_e32 v8, 4, v12
	v_mov_b32_e32 v9, v1
	v_lshl_add_u64 v[6:7], v[6:7], 0, v[8:9]
	global_load_dwordx4 v[62:65], v[6:7], off
	global_load_dwordx4 v[58:61], v[6:7], off offset:32
	global_load_dwordx4 v[54:57], v[6:7], off offset:64
	global_load_dwordx4 v[50:53], v[6:7], off offset:96
	global_load_dwordx4 v[46:49], v[6:7], off offset:128
	global_load_dwordx4 v[42:45], v[6:7], off offset:160
	global_load_dwordx4 v[38:41], v[6:7], off offset:192
	global_load_dwordx4 v[34:37], v[6:7], off offset:224
	v_add_u32_e32 v6, s8, v114
	v_ashrrev_i32_e32 v7, 31, v6
	s_waitcnt lgkmcnt(0)
	v_lshl_add_u64 v[6:7], v[6:7], 2, s[4:5]
	global_load_dword v116, v[6:7], off
	v_ashrrev_i32_e32 v7, 2, v218
	v_lshlrev_b32_e32 v6, 5, v218
	v_mad_i64_i32 v[2:3], s[8:9], v7, s38, v[2:3]
	v_and_b32_e32 v6, 0x60, v6
	v_lshl_add_u64 v[2:3], v[2:3], 0, s[34:35]
	v_lshlrev_b32_e32 v10, 1, v6
	v_mov_b32_e32 v11, v1
	v_lshl_add_u64 v[2:3], v[2:3], 0, v[10:11]
	global_load_dwordx4 v[98:101], v[2:3], off offset:1584
	global_load_dwordx4 v[102:105], v[2:3], off offset:1568
	global_load_dwordx4 v[106:109], v[2:3], off offset:1552
	global_load_dwordx4 v[110:113], v[2:3], off offset:1536
	v_lshl_add_u64 v[4:5], s[6:7], 0, v[4:5]
	v_lshl_add_u64 v[122:123], v[4:5], 0, v[8:9]
	s_movk_i32 s6, 0x140
	v_lshrrev_b32_e32 v5, 2, v218
	v_mul_lo_u32 v4, v7, s6
	v_and_or_b32 v0, v5, 3, v0
	s_lshl_b32 s6, s23, 6
	v_lshlrev_b32_e32 v5, 1, v190
	v_mad_i64_i32 v[120:121], s[8:9], v7, s38, 0
	v_and_b32_e32 v3, 3, v218
	v_mul_u32_u24_e32 v0, 0x140, v0
	s_add_i32 s6, s6, 0
	v_lshlrev_b32_e32 v7, 3, v190
	v_and_b32_e32 v5, 32, v5
	v_mad_i64_i32 v[118:119], s[8:9], v114, s38, 0
	v_lshlrev_b32_e32 v2, 2, v12
	v_lshl_add_u32 v117, v3, 7, 0
	v_add_u32_e32 v4, 0, v4
	v_lshlrev_b32_e32 v3, 6, v3
	v_and_b32_e32 v7, 24, v7
	v_add3_u32 v5, s6, v0, v5
	s_lshl_b64 s[6:7], s[36:37], 1
	v_lshlrev_b32_e32 v0, 1, v2
	v_lshlrev_b32_e32 v124, 1, v6
	v_add_u32_e32 v196, v4, v3
	v_add_u32_e32 v198, v5, v7
	s_mov_b32 s9, s33
	s_waitcnt vmcnt(0)
	s_barrier
.LBB0_69:
	s_add_i32 s10, s9, s44
	s_waitcnt vmcnt(8)
	v_lshlrev_b32_e32 v6, 16, v113
	v_and_b32_e32 v7, 0xffff0000, v113
	v_lshlrev_b32_e32 v10, 16, v111
	v_and_b32_e32 v11, 0xffff0000, v111
	v_lshlrev_b32_e32 v12, 16, v110
	v_and_b32_e32 v13, 0xffff0000, v110
	v_lshlrev_b32_e32 v8, 16, v112
	v_and_b32_e32 v9, 0xffff0000, v112
	s_cmpk_lt_i32 s10, 0x600
	v_pk_mul_f32 v[70:71], v[6:7], v[6:7]
	v_pk_mul_f32 v[74:75], v[10:11], v[10:11]
	v_pk_mul_f32 v[76:77], v[12:13], v[12:13]
	v_pk_mul_f32 v[72:73], v[8:9], v[8:9]
	s_cselect_b32 s11, s10, s9
	v_add_f32_e32 v70, v70, v71
	v_add_f32_e32 v71, v74, v75
	v_add_f32_e32 v74, v76, v77
	v_lshlrev_b32_e32 v20, 16, v106
	v_and_b32_e32 v21, 0xffff0000, v106
	v_add_f32_e32 v72, v72, v73
	s_mul_hi_i32 s23, s11, 0x2aaaaaab
	v_add_f32_e32 v71, v74, v71
	v_lshlrev_b32_e32 v18, 16, v107
	v_and_b32_e32 v19, 0xffff0000, v107
	v_pk_mul_f32 v[84:85], v[20:21], v[20:21]
	s_lshr_b32 s34, s23, 31
	s_ashr_i32 s23, s23, 4
	v_add_f32_e32 v71, v72, v71
	v_lshlrev_b32_e32 v16, 16, v108
	v_and_b32_e32 v17, 0xffff0000, v108
	v_pk_mul_f32 v[82:83], v[18:19], v[18:19]
	v_add_f32_e32 v73, v84, v85
	s_add_i32 s34, s23, s34
	v_add_f32_e32 v70, v70, v71
	v_and_b32_e32 v5, 0xffff0000, v101
	v_and_b32_e32 v4, 0xffff0000, v100
	v_lshlrev_b32_e32 v14, 16, v109
	v_and_b32_e32 v15, 0xffff0000, v109
	v_and_b32_e32 v27, 0xffff0000, v103
	v_and_b32_e32 v29, 0xffff0000, v102
	v_pk_mul_f32 v[80:81], v[16:17], v[16:17]
	v_add_f32_e32 v75, v82, v83
	s_mul_i32 s23, s34, 0x60
	v_add_f32_e32 v70, v73, v70
	v_lshlrev_b32_e32 v33, 16, v101
	v_lshlrev_b32_e32 v32, 16, v100
	v_lshlrev_b32_e32 v26, 16, v103
; #define LAS __attribute__((address_space(3)))
; __device__ __forceinline__ void gmlp_compute(LAS unsigned char* lds, const GmlpRegs& R, bf16_t* cat, int u, int tid, int lane, int t, int h, int cb0) {
;     constexpr int VP = 320, GOFF = 49152;
;     const int b = u / 96, rem = u % 96, n = rem / 6, g = rem % 6;
;     {
;         const int row = tid >> 2, qtr = tid & 3;
;         float ss = 0.f;
; #pragma unroll
;         for (int j = 0; j < 4; ++j)
; #pragma unroll
;             for (int e = 0; e < 4; ++e) { const float x = bf_lo(R.v[j][e]), y = bf_hi(R.v[j][e]); ss += x * x + y * y; }
;         ss += __shfl_xor(ss, 1); ss += __shfl_xor(ss, 2);
;         const float rs = rsqrtf(ss * (1.f / 128.f) + EPS);
;         LAS const unsigned char* gp = lds + GOFF + (g * 128 + qtr * 32) * 4;
;         LAS unsigned char* dst = lds + row * VP + qtr * 64;
; __device__ __forceinline__ void gmlp_phase(LAS unsigned char* lds, const bf16_t* zb, const bf16_t* wsb, const float* bsall, const float* vgall, bf16_t* cat, int vcu, int G, const int tid) {
;     ...
;         const int un = u + G; const bool hn = un < 1536;
;         GmlpRegs B; gmlp_load(B, zb, wsb, bsall, hn ? un : u, tid, t, h, cb0);
	v_lshlrev_b32_e32 v28, 16, v102
	v_pk_mul_f32 v[68:69], v[4:5], v[4:5]
	v_pk_mul_f32 v[78:79], v[14:15], v[14:15]
	v_mov_b32_e32 v92, v27
	v_mov_b32_e32 v93, v29
	v_add_f32_e32 v76, v80, v81
	s_sub_i32 s11, s11, s23
	v_add_f32_e32 v70, v75, v70
	v_and_b32_e32 v3, 0xffff0000, v99
	v_and_b32_e32 v2, 0xffff0000, v98
	v_and_b32_e32 v23, 0xffff0000, v105
	v_and_b32_e32 v25, 0xffff0000, v104
	v_mov_b32_e32 v90, v26
	v_mov_b32_e32 v91, v28
	v_mov_b32_e32 v192, v32
	v_mov_b32_e32 v193, v4
	v_mov_b32_e32 v4, v33
	v_pk_fma_f32 v[32:33], v[32:33], v[32:33], v[68:69]
	v_pk_mul_f32 v[68:69], v[92:93], v[92:93]
	v_add_f32_e32 v77, v78, v79
	s_mul_i32 s23, s11, 43
	v_add_f32_e32 v70, v76, v70
	v_lshlrev_b32_e32 v31, 16, v99
	v_lshlrev_b32_e32 v30, 16, v98
	v_lshlrev_b32_e32 v22, 16, v105
	v_lshlrev_b32_e32 v24, 16, v104
	v_pk_mul_f32 v[66:67], v[2:3], v[2:3]
	v_mov_b32_e32 v88, v23
	v_mov_b32_e32 v89, v25
	v_pk_fma_f32 v[68:69], v[90:91], v[90:91], v[68:69]
	s_bfe_u32 s36, s23, 0x1000f
	s_bfe_u32 s23, s23, 0x80008
	v_add_f32_e32 v70, v77, v70
	v_mov_b32_e32 v86, v22
	v_mov_b32_e32 v87, v24
	v_mov_b32_e32 v178, v30
	v_mov_b32_e32 v179, v2
	v_mov_b32_e32 v2, v31
	v_pk_fma_f32 v[30:31], v[30:31], v[30:31], v[66:67]
	v_pk_mul_f32 v[66:67], v[88:89], v[88:89]
	s_add_i32 s23, s23, s36
	v_add_f32_e32 v69, v69, v70
	v_pk_fma_f32 v[66:67], v[86:87], v[86:87], v[66:67]
	s_sext_i32_i8 s37, s23
	s_mul_i32 s23, s23, 6
	v_add_f32_e32 v68, v68, v69
	s_ashr_i32 s35, s34, 31
	s_sub_i32 s36, s11, s23
	s_lshl_b32 s11, s37, 7
	v_add_f32_e32 v67, v67, v68
	s_lshl_b64 s[34:35], s[34:35], 11
	s_ashr_i32 s37, s11, 31
	v_add_f32_e32 v66, v66, v67
	s_add_u32 s11, s34, s11
	v_add_f32_e32 v30, v30, v66
	s_addc_u32 s34, s35, s37
	v_add_f32_e32 v30, v31, v30
	s_mul_hi_u32 s35, s11, 0xe00
	s_mulk_i32 s34, 0xe00
	v_add_f32_e32 v30, v32, v30
	s_mulk_i32 s11, 0xe00
	s_add_i32 s35, s35, s34
	v_add_f32_e32 v100, v33, v30
	s_sext_i32_i8 s23, s36
	s_add_u32 s34, s24, s11
	ds_bpermute_b32 v101, v219, v100
	s_addc_u32 s35, s25, s35
	s_lshl_b32 s38, s23, 7
	s_bfe_i64 s[36:37], s[36:37], 0x80000
	s_ashr_i32 s39, s38, 31
	v_add_u32_e32 v32, s38, v114
	s_lshl_b64 s[36:37], s[36:37], 15
	v_lshl_add_u64 v[30:31], s[34:35], 0, v[118:119]
	v_lshl_add_u64 v[98:99], s[34:35], 0, v[120:121]
	s_lshl_b64 s[34:35], s[38:39], 1
	v_ashrrev_i32_e32 v33, 31, v32
	v_mov_b32_e32 v125, v1
	v_lshl_add_u64 v[66:67], v[122:123], 0, s[36:37]
	v_lshl_add_u64 v[32:33], v[32:33], 2, s[4:5]
	v_lshl_add_u64 v[98:99], v[98:99], 0, s[34:35]
	global_load_dwordx4 v[78:81], v[66:67], off
	global_load_dwordx4 v[82:85], v[66:67], off offset:32
	global_load_dwordx4 v[86:89], v[66:67], off offset:64
	global_load_dwordx4 v[90:93], v[66:67], off offset:96
	global_load_dwordx4 v[94:97], v[66:67], off offset:128
	global_load_dwordx4 v[70:73], v[66:67], off offset:160
	global_load_dwordx4 v[74:77], v[66:67], off offset:192
	s_nop 0
	global_load_dwordx4 v[66:69], v[66:67], off offset:224
	s_mul_hi_i32 s8, s9, 0x2aaaaaab
	global_load_dword v200, v[32:33], off
	v_lshl_add_u64 v[32:33], v[98:99], 0, v[124:125]
	s_waitcnt lgkmcnt(0)
	v_add_f32_e32 v125, v100, v101
	global_load_dwordx4 v[98:101], v[32:33], off offset:1584
	global_load_dwordx4 v[102:105], v[32:33], off offset:1568
	global_load_dwordx4 v[106:109], v[32:33], off offset:1552
	global_load_dwordx4 v[110:113], v[32:33], off offset:1536
	ds_bpermute_b32 v32, v220, v125
	s_lshr_b32 s11, s8, 31
	s_ashr_i32 s8, s8, 4
	s_add_i32 s8, s8, s11
	s_mul_i32 s11, s8, 0xffffffa0
	s_add_i32 s9, s9, s11
	s_mul_i32 s11, s9, 43
	s_waitcnt lgkmcnt(0)
	v_add_f32_e32 v125, v125, v32
	s_bfe_u32 s23, s11, 0x1000f
	s_bfe_u32 s11, s11, 0x80008
	v_fmamk_f32 v125, v125, 0x3c000000, v182
	s_add_i32 s23, s11, s23
	v_mul_f32_e32 v194, 0x4b800000, v125
	v_cmp_gt_f32_e32 vcc, s89, v125
	s_mul_i32 s11, s23, 6
	v_lshl_add_u64 v[30:31], v[30:31], 0, s[34:35]
	v_cndmask_b32_e32 v125, v125, v194, vcc
	s_sub_i32 s9, s9, s11
	v_rsq_f32_e32 v125, v125
	v_lshl_add_u64 v[30:31], v[30:31], 0, v[0:1]
	s_sext_i32_i8 s11, s9
	v_lshl_add_u64 v[30:31], v[30:31], 0, s[6:7]
	v_lshl_add_u32 v149, s11, 9, v117
	v_lshlrev_b32_e32 v136, 16, v160
	v_and_b32_e32 v137, 0xffff0000, v160
	v_lshlrev_b32_e32 v138, 16, v161
	v_and_b32_e32 v139, 0xffff0000, v161
	v_lshlrev_b32_e32 v140, 16, v162
	v_and_b32_e32 v141, 0xffff0000, v162
	v_lshlrev_b32_e32 v142, 16, v163
	v_and_b32_e32 v143, 0xffff0000, v163
	v_lshlrev_b32_e32 v144, 16, v164
	v_and_b32_e32 v145, 0xffff0000, v164
	v_lshlrev_b32_e32 v146, 16, v165
	v_and_b32_e32 v147, 0xffff0000, v165
	global_load_dwordx2 v[160:161], v[30:31], off
	global_load_dwordx2 v[162:163], v[30:31], off offset:16
	global_load_dwordx2 v[164:165], v[30:31], off offset:32
	global_load_dwordx2 v[150:151], v[30:31], off offset:48
	global_load_dwordx2 v[152:153], v[30:31], off offset:64
	global_load_dwordx2 v[154:155], v[30:31], off offset:80
	global_load_dwordx2 v[156:157], v[30:31], off offset:96
	global_load_dwordx2 v[158:159], v[30:31], off offset:112
	ds_read_b128 v[30:33], v149 offset:49152
	ds_read_b128 v[166:169], v149 offset:49168
	ds_read_b128 v[170:173], v149 offset:49184
	ds_read_b128 v[174:177], v149 offset:49200
	v_mul_f32_e32 v194, 0x45800000, v125
	v_cndmask_b32_e32 v194, v125, v194, vcc
	v_pk_mul_f32 v[12:13], v[194:195], v[12:13] op_sel_hi:[0,1]
	v_pk_mul_f32 v[10:11], v[194:195], v[10:11] op_sel_hi:[0,1]
	v_pk_mul_f32 v[8:9], v[194:195], v[8:9] op_sel_hi:[0,1]
	v_pk_mul_f32 v[6:7], v[194:195], v[6:7] op_sel_hi:[0,1]
	v_pk_mul_f32 v[20:21], v[194:195], v[20:21] op_sel_hi:[0,1]
	v_pk_mul_f32 v[18:19], v[194:195], v[18:19] op_sel_hi:[0,1]
	v_pk_mul_f32 v[16:17], v[194:195], v[16:17] op_sel_hi:[0,1]
	v_pk_mul_f32 v[14:15], v[194:195], v[14:15] op_sel_hi:[0,1]
	v_pk_mul_f32 v[28:29], v[194:195], v[28:29] op_sel_hi:[0,1]
	v_pk_mul_f32 v[26:27], v[194:195], v[26:27] op_sel_hi:[0,1]
	v_pk_mul_f32 v[24:25], v[194:195], v[24:25] op_sel_hi:[0,1]
	v_pk_mul_f32 v[22:23], v[194:195], v[22:23] op_sel_hi:[0,1]
	v_pk_mul_f32 v[178:179], v[194:195], v[178:179] op_sel_hi:[0,1]
	v_pk_mul_f32 v[202:203], v[194:195], v[2:3] op_sel_hi:[0,1]
	v_pk_mul_f32 v[192:193], v[194:195], v[192:193] op_sel_hi:[0,1]
	v_pk_mul_f32 v[194:195], v[194:195], v[4:5] op_sel_hi:[0,1]
	s_waitcnt lgkmcnt(3)
; #define LAS __attribute__((address_space(3)))
; __device__ __forceinline__ unsigned pk_bf16(float lo, float hi) { f32x2 v = {lo, hi}; bf16x2_t b = __builtin_convertvector(v, bf16x2_t); return __builtin_bit_cast(unsigned, b); }
; #define MFMA32(a, b, c) __builtin_amdgcn_mfma_f32_32x32x16_bf16((a), (b), (c), 0, 0, 0)
; __device__ __forceinline__ void gmlp_compute(LAS unsigned char* lds, const GmlpRegs& R, bf16_t* cat, int u, int tid, int lane, int t, int h, int cb0) {
;     ...
;         LAS unsigned char* dst = lds + row * VP + qtr * 64;
; #pragma unroll
;         for (int j = 0; j < 4; ++j) {
;             const f32x4 g0 = *(LAS const f32x4*)(gp + 32 * j), g1 = *(LAS const f32x4*)(gp + 32 * j + 16);
;             u32x4 o;
;             o.x = pk_bf16(bf_lo(R.v[j].x) * rs * g0[0], bf_hi(R.v[j].x) * rs * g0[1]); o.y = pk_bf16(bf_lo(R.v[j].y) * rs * g0[2], bf_hi(R.v[j].y) * rs * g0[3]);
;             o.z = pk_bf16(bf_lo(R.v[j].z) * rs * g1[0], bf_hi(R.v[j].z) * rs * g1[1]); o.w = pk_bf16(bf_lo(R.v[j].w) * rs * g1[2], bf_hi(R.v[j].w) * rs * g1[3]);
;             *(LAS u32x4*)(dst + 16 * j) = o;
;         }
;     }
;     __syncthreads();
;     const int q4 = (lane & 15) >> 2, p4 = lane & 3, blk = (lane >> 4) & 1;
;     LAS const char* vb = (LAS const char*)lds + (8 * h + q4) * VP + (cb0 * 32 + 16 * blk) * 2 + 8 * p4;
;     f32x16 a0, a1;
; #pragma unroll
;     for (int i = 0; i < 16; ++i) { a0[i] = 0.f; a1[i] = 0.f; }
; #pragma unroll
;     for (int ks = 0; ks < 8; ++ks) {
;         const bf16x8 wf = __builtin_bit_cast(bf16x8, R.w[ks]);
;         const bf16x8 v0 = vtr8(vb + ks * 16 * VP, 4 * VP), v1 = vtr8(vb + ks * 16 * VP + 64, 4 * VP);
;         a0 = MFMA32(v0, wf, a0); a1 = MFMA32(v1, wf, a1);
;     }
;     bf16_t* orow = cat + ((size_t)b * SEQ + n * 128 + t) * DM + g * 128 + 4 * h;
	v_pk_mul_f32 v[2:3], v[30:31], v[12:13]
	v_pk_mul_f32 v[4:5], v[32:33], v[10:11]
	s_waitcnt lgkmcnt(2)
	v_pk_mul_f32 v[8:9], v[166:167], v[8:9]
	v_pk_mul_f32 v[6:7], v[168:169], v[6:7]
	s_waitcnt lgkmcnt(1)
	v_pk_mul_f32 v[10:11], v[170:171], v[20:21]
	v_pk_mul_f32 v[12:13], v[172:173], v[18:19]
	s_waitcnt lgkmcnt(0)
	v_pk_mul_f32 v[16:17], v[174:175], v[16:17]
	v_pk_mul_f32 v[14:15], v[176:177], v[14:15]
	v_cvt_pk_bf16_f32 v2, v2, v3
	v_cvt_pk_bf16_f32 v3, v4, v5
	v_cvt_pk_bf16_f32 v4, v8, v9
	v_cvt_pk_bf16_f32 v5, v6, v7
	v_cvt_pk_bf16_f32 v6, v10, v11
	v_cvt_pk_bf16_f32 v7, v12, v13
	v_cvt_pk_bf16_f32 v8, v16, v17
	v_cvt_pk_bf16_f32 v9, v14, v15
	ds_write_b128 v196, v[2:5]
	ds_write_b128 v196, v[6:9] offset:16
	ds_read_b128 v[2:5], v149 offset:49216
	ds_read_b128 v[6:9], v149 offset:49232
	v_lshlrev_b32_e32 v168, 16, v132
	v_and_b32_e32 v169, 0xffff0000, v132
	v_lshlrev_b32_e32 v170, 16, v133
	s_waitcnt lgkmcnt(1)
	v_pk_mul_f32 v[2:3], v[2:3], v[28:29]
	v_pk_mul_f32 v[4:5], v[4:5], v[26:27]
	s_waitcnt lgkmcnt(0)
	v_pk_mul_f32 v[6:7], v[6:7], v[24:25]
	v_pk_mul_f32 v[8:9], v[8:9], v[22:23]
	v_cvt_pk_bf16_f32 v2, v2, v3
	v_cvt_pk_bf16_f32 v3, v4, v5
	v_cvt_pk_bf16_f32 v4, v6, v7
	v_cvt_pk_bf16_f32 v5, v8, v9
	ds_write_b128 v196, v[2:5] offset:32
	ds_read_b128 v[2:5], v149 offset:49248
	ds_read_b128 v[6:9], v149 offset:49264
	v_and_b32_e32 v171, 0xffff0000, v133
	s_ashr_i32 s9, s8, 31
	s_lshl_b64 s[34:35], s[8:9], 11
	s_waitcnt lgkmcnt(1)
	v_pk_mul_f32 v[2:3], v[178:179], v[2:3]
	v_pk_mul_f32 v[4:5], v[202:203], v[4:5]
	s_waitcnt lgkmcnt(0)
	v_pk_mul_f32 v[6:7], v[192:193], v[6:7]
	v_pk_mul_f32 v[8:9], v[194:195], v[8:9]
	v_cvt_pk_bf16_f32 v2, v2, v3
	v_cvt_pk_bf16_f32 v3, v4, v5
	v_cvt_pk_bf16_f32 v4, v6, v7
	v_cvt_pk_bf16_f32 v5, v8, v9
	ds_write_b128 v196, v[2:5] offset:48
	s_waitcnt lgkmcnt(0)
	s_barrier
	ds_read_b64_tr_b16 v[2:3], v198
	ds_read_b64_tr_b16 v[4:5], v198 offset:1280
	ds_read_b64_tr_b16 v[20:21], v198 offset:1344
	ds_read_b64_tr_b16 v[18:19], v198 offset:64
	ds_read_b64_tr_b16 v[172:173], v198 offset:5120
	s_waitcnt lgkmcnt(3)
	v_mfma_f32_32x32x16_bf16 v[2:17], v[2:5], v[62:65], 0
	s_sext_i32_i8 s8, s23
	s_lshl_b32 s8, s8, 7
	s_ashr_i32 s23, s8, 31
	s_lshl_b32 s36, s11, 7
	s_add_u32 s34, s8, s34
	s_addc_u32 s35, s23, s35
	s_ashr_i32 s37, s36, 31
	s_waitcnt lgkmcnt(1)
	v_mfma_f32_32x32x16_bf16 v[18:33], v[18:21], v[62:65], 0
	ds_read_b64_tr_b16 v[174:175], v198 offset:6400
	ds_read_b64_tr_b16 v[64:65], v198 offset:6464
	ds_read_b64_tr_b16 v[62:63], v198 offset:5184
	v_lshlrev_b32_e32 v176, 16, v128
	v_and_b32_e32 v177, 0xffff0000, v128
	v_lshlrev_b32_e32 v178, 16, v129
	v_and_b32_e32 v179, 0xffff0000, v129
	v_lshlrev_b32_e32 v192, 16, v126
	v_and_b32_e32 v193, 0xffff0000, v126
	s_waitcnt lgkmcnt(2)
	v_mfma_f32_32x32x16_bf16 v[2:17], v[172:175], v[58:61], v[2:17]
	v_lshlrev_b32_e32 v172, 16, v130
	v_and_b32_e32 v173, 0xffff0000, v130
	v_lshlrev_b32_e32 v174, 16, v131
	v_and_b32_e32 v175, 0xffff0000, v131
	ds_read_b64_tr_b16 v[130:131], v198 offset:10240
	v_lshlrev_b32_e32 v194, 16, v127
	v_and_b32_e32 v195, 0xffff0000, v127
	s_waitcnt lgkmcnt(1)
	v_mfma_f32_32x32x16_bf16 v[18:33], v[62:65], v[58:61], v[18:33]
	ds_read_b64_tr_b16 v[132:133], v198 offset:11520
	ds_read_b64_tr_b16 v[60:61], v198 offset:11584
	ds_read_b64_tr_b16 v[58:59], v198 offset:10304
	ds_read_b64_tr_b16 v[62:63], v198 offset:15360
	v_lshlrev_b32_e32 v148, 16, v134
	v_and_b32_e32 v149, 0xffff0000, v134
	v_lshlrev_b32_e32 v166, 16, v135
	v_and_b32_e32 v167, 0xffff0000, v135
	s_mov_b32 s9, s10
	s_waitcnt lgkmcnt(3)
	v_mfma_f32_32x32x16_bf16 v[2:17], v[130:133], v[54:57], v[2:17]
	s_cmpk_gt_i32 s10, 0x5ff
	s_waitcnt vmcnt(4)
	v_mov_b64_e32 v[134:135], v[150:151]
	s_waitcnt vmcnt(3)
	v_mov_b64_e32 v[132:133], v[152:153]
	s_waitcnt vmcnt(2)
	v_mov_b64_e32 v[130:131], v[154:155]
	s_waitcnt lgkmcnt(1)
	v_mfma_f32_32x32x16_bf16 v[18:33], v[58:61], v[54:57], v[18:33]
	ds_read_b64_tr_b16 v[64:65], v198 offset:16640
	ds_read_b64_tr_b16 v[56:57], v198 offset:16704
	ds_read_b64_tr_b16 v[54:55], v198 offset:15424
	ds_read_b64_tr_b16 v[58:59], v198 offset:20480
	s_waitcnt lgkmcnt(3)
	v_mfma_f32_32x32x16_bf16 v[2:17], v[62:65], v[50:53], v[2:17]
	v_mov_b64_e32 v[62:63], v[78:79]
	v_mov_b64_e32 v[64:65], v[80:81]
	s_waitcnt lgkmcnt(1)
	v_mfma_f32_32x32x16_bf16 v[18:33], v[54:57], v[50:53], v[18:33]
	ds_read_b64_tr_b16 v[60:61], v198 offset:21760
	ds_read_b64_tr_b16 v[52:53], v198 offset:21824
	ds_read_b64_tr_b16 v[50:51], v198 offset:20544
	ds_read_b64_tr_b16 v[54:55], v198 offset:25600
	s_waitcnt lgkmcnt(3)
	v_mfma_f32_32x32x16_bf16 v[2:17], v[58:61], v[46:49], v[2:17]
	v_mov_b64_e32 v[58:59], v[82:83]
	v_mov_b64_e32 v[60:61], v[84:85]
	s_waitcnt lgkmcnt(1)
; __device__ __forceinline__ unsigned pk_bf16(float lo, float hi) { f32x2 v = {lo, hi}; bf16x2_t b = __builtin_convertvector(v, bf16x2_t); return __builtin_bit_cast(unsigned, b); }
; #define MFMA32(a, b, c) __builtin_amdgcn_mfma_f32_32x32x16_bf16((a), (b), (c), 0, 0, 0)
; __device__ __forceinline__ void gmlp_compute(LAS unsigned char* lds, const GmlpRegs& R, bf16_t* cat, int u, int tid, int lane, int t, int h, int cb0) {
;     ...
;         const bf16x8 wf = __builtin_bit_cast(bf16x8, R.w[ks]);
;         const bf16x8 v0 = vtr8(vb + ks * 16 * VP, 4 * VP), v1 = vtr8(vb + ks * 16 * VP + 64, 4 * VP);
;         a0 = MFMA32(v0, wf, a0); a1 = MFMA32(v1, wf, a1);
;     }
;     bf16_t* orow = cat + ((size_t)b * SEQ + n * 128 + t) * DM + g * 128 + 4 * h;
;     const float bias = R.bias;
; #pragma unroll
;     for (int cbi = 0; cbi < 2; ++cbi)
; #pragma unroll
;         for (int gq = 0; gq < 4; ++gq) {
;             const int c0 = (cb0 + cbi) * 32 + 8 * gq;
;             const u32x2 uu = R.uv[cbi * 4 + gq];
;             const f32x16& a = cbi ? a1 : a0;
;             u32x2 wv; wv.x = pk_bf16(bf_lo(uu.x) * (a[4 * gq] + bias), bf_hi(uu.x) * (a[4 * gq + 1] + bias));
;             wv.y = pk_bf16(bf_lo(uu.y) * (a[4 * gq + 2] + bias), bf_hi(uu.y) * (a[4 * gq + 3] + bias));
;             *(u32x2*)(orow + c0) = wv;
;         }
;     __syncthreads();
	v_mfma_f32_32x32x16_bf16 v[18:33], v[50:53], v[46:49], v[18:33]
	v_lshl_add_u64 v[50:51], s[34:35], 0, v[114:115]
	v_lshlrev_b64 v[50:51], 11, v[50:51]
	ds_read_b64_tr_b16 v[56:57], v198 offset:26880
	ds_read_b64_tr_b16 v[48:49], v198 offset:26944
	ds_read_b64_tr_b16 v[46:47], v198 offset:25664
	v_lshl_add_u64 v[50:51], s[12:13], 0, v[50:51]
	v_lshl_add_u64 v[50:51], s[36:37], 1, v[50:51]
	v_lshl_add_u64 v[50:51], v[50:51], 0, v[0:1]
	v_lshl_add_u64 v[206:207], v[50:51], 0, s[6:7]
	ds_read_b64_tr_b16 v[50:51], v198 offset:30720
	s_waitcnt lgkmcnt(3)
	v_mfma_f32_32x32x16_bf16 v[2:17], v[54:57], v[42:45], v[2:17]
	v_mov_b64_e32 v[54:55], v[86:87]
	v_mov_b64_e32 v[56:57], v[88:89]
	s_waitcnt lgkmcnt(1)
	v_mfma_f32_32x32x16_bf16 v[18:33], v[46:49], v[42:45], v[18:33]
	ds_read_b64_tr_b16 v[52:53], v198 offset:32000
	ds_read_b64_tr_b16 v[44:45], v198 offset:32064
	ds_read_b64_tr_b16 v[42:43], v198 offset:30784
	ds_read_b64_tr_b16 v[126:127], v198 offset:35840
	ds_read_b64_tr_b16 v[128:129], v198 offset:37120
	ds_read_b64_tr_b16 v[204:205], v198 offset:37184
	ds_read_b64_tr_b16 v[202:203], v198 offset:35904
	v_mov_b64_e32 v[46:47], v[94:95]
	v_mov_b64_e32 v[48:49], v[96:97]
	s_waitcnt lgkmcnt(6)
	v_mfma_f32_32x32x16_bf16 v[2:17], v[50:53], v[38:41], v[2:17]
	v_mov_b64_e32 v[50:51], v[90:91]
	v_mov_b64_e32 v[52:53], v[92:93]
	s_waitcnt lgkmcnt(4)
	v_mfma_f32_32x32x16_bf16 v[18:33], v[42:45], v[38:41], v[18:33]
	v_mov_b64_e32 v[42:43], v[70:71]
	v_mov_b64_e32 v[38:39], v[74:75]
	v_mov_b64_e32 v[44:45], v[72:73]
	v_mov_b64_e32 v[40:41], v[76:77]
	s_waitcnt lgkmcnt(2)
	v_mfma_f32_32x32x16_bf16 v[2:17], v[126:129], v[34:37], v[2:17]
	s_waitcnt vmcnt(1)
	v_mov_b64_e32 v[128:129], v[156:157]
	s_waitcnt vmcnt(0)
	v_mov_b64_e32 v[126:127], v[158:159]
	s_waitcnt lgkmcnt(0)
	v_mfma_f32_32x32x16_bf16 v[18:33], v[202:205], v[34:37], v[18:33]
	s_nop 5
	v_add_f32_e64 v2, v116, v2
	v_add_f32_e64 v3, v116, v3
	v_add_f32_e64 v4, v116, v4
	v_add_f32_e64 v5, v116, v5
	v_mov_b64_e32 v[34:35], v[66:67]
	v_pk_add_f32 v[6:7], v[116:117], v[6:7] op_sel_hi:[0,1]
	v_pk_add_f32 v[8:9], v[116:117], v[8:9] op_sel_hi:[0,1]
	v_pk_add_f32 v[10:11], v[116:117], v[10:11] op_sel_hi:[0,1]
	v_pk_add_f32 v[12:13], v[116:117], v[12:13] op_sel_hi:[0,1]
	v_pk_add_f32 v[14:15], v[116:117], v[14:15] op_sel_hi:[0,1]
	v_pk_add_f32 v[16:17], v[116:117], v[16:17] op_sel_hi:[0,1]
	v_pk_add_f32 v[18:19], v[116:117], v[18:19] op_sel_hi:[0,1]
	v_pk_add_f32 v[20:21], v[116:117], v[20:21] op_sel_hi:[0,1]
	v_pk_add_f32 v[22:23], v[116:117], v[22:23] op_sel_hi:[0,1]
	v_pk_add_f32 v[24:25], v[116:117], v[24:25] op_sel_hi:[0,1]
	v_pk_add_f32 v[26:27], v[116:117], v[26:27] op_sel_hi:[0,1]
	v_pk_add_f32 v[28:29], v[116:117], v[28:29] op_sel_hi:[0,1]
	v_pk_add_f32 v[30:31], v[116:117], v[30:31] op_sel_hi:[0,1]
	v_pk_add_f32 v[32:33], v[116:117], v[32:33] op_sel_hi:[0,1]
	v_pk_mul_f32 v[2:3], v[2:3], v[136:137]
	v_pk_mul_f32 v[4:5], v[4:5], v[138:139]
	v_mov_b64_e32 v[36:37], v[68:69]
	v_mov_b32_e32 v116, v200
	v_pk_mul_f32 v[6:7], v[6:7], v[140:141]
	v_pk_mul_f32 v[8:9], v[8:9], v[142:143]
	v_pk_mul_f32 v[10:11], v[10:11], v[144:145]
	v_pk_mul_f32 v[12:13], v[12:13], v[146:147]
	v_pk_mul_f32 v[14:15], v[14:15], v[148:149]
	v_pk_mul_f32 v[16:17], v[16:17], v[166:167]
	v_pk_mul_f32 v[18:19], v[18:19], v[168:169]
	v_pk_mul_f32 v[20:21], v[20:21], v[170:171]
	v_pk_mul_f32 v[22:23], v[22:23], v[172:173]
	v_pk_mul_f32 v[24:25], v[24:25], v[174:175]
	v_pk_mul_f32 v[26:27], v[26:27], v[176:177]
	v_pk_mul_f32 v[28:29], v[28:29], v[178:179]
	v_pk_mul_f32 v[30:31], v[30:31], v[192:193]
	v_pk_mul_f32 v[32:33], v[32:33], v[194:195]
	v_cvt_pk_bf16_f32 v2, v2, v3
	v_cvt_pk_bf16_f32 v3, v4, v5
	v_cvt_pk_bf16_f32 v4, v6, v7
	v_cvt_pk_bf16_f32 v5, v8, v9
	v_cvt_pk_bf16_f32 v6, v10, v11
	v_cvt_pk_bf16_f32 v7, v12, v13
	v_cvt_pk_bf16_f32 v8, v14, v15
	v_cvt_pk_bf16_f32 v9, v16, v17
	v_cvt_pk_bf16_f32 v10, v18, v19
	v_cvt_pk_bf16_f32 v11, v20, v21
	v_cvt_pk_bf16_f32 v12, v22, v23
	v_cvt_pk_bf16_f32 v13, v24, v25
	v_cvt_pk_bf16_f32 v14, v26, v27
	v_cvt_pk_bf16_f32 v15, v28, v29
	v_cvt_pk_bf16_f32 v16, v30, v31
	v_cvt_pk_bf16_f32 v17, v32, v33
	global_store_dwordx2 v[206:207], v[2:3], off
	global_store_dwordx2 v[206:207], v[4:5], off offset:16
	global_store_dwordx2 v[206:207], v[6:7], off offset:32
	global_store_dwordx2 v[206:207], v[8:9], off offset:48
	global_store_dwordx2 v[206:207], v[10:11], off offset:64
	global_store_dwordx2 v[206:207], v[12:13], off offset:80
	global_store_dwordx2 v[206:207], v[14:15], off offset:96
	global_store_dwordx2 v[206:207], v[16:17], off offset:112
	s_barrier
	s_cbranch_scc0 .LBB0_69
